# speedup vs baseline: 1.3588x; 1.0029x over previous
; #define LAS __attribute__((address_space(3)))
; __device__ __forceinline__ unsigned pk2(float lo, float hi) { return f2bf(lo) | (f2bf(hi) << 16); }
; __device__ __forceinline__ s16x4 tr_read(const LAS unsigned short* p) { return __builtin_amdgcn_ds_read_tr16_b64_v4i16((LAS s16x4*)p); }
; __device__ __forceinline__ bf16x8 pack8(f32x4 a, f32x4 b) { u32x4 w; w.x = pk2(a[0], a[1]); w.y = pk2(a[2], a[3]); w.z = pk2(b[0], b[1]); w.w = pk2(b[2], b[3]); return __builtin_bit_cast(bf16x8, w); }
; template <int KIND, int MODE>
; __device__ __forceinline__ void scan_unit(Frame& F, int layer, int h, int vhalf, int grp) {
;     ...
;                 const int t = 16 * ttile + li; float p[4]; float rs = 0.f;
;                 float mt = 0.f; f32x4 cs = (f32x4){0.f, 0.f, 0.f, 0.f};
;                 if (KIND) { mt = X[64 + t]; cs = *(const LAS f32x4*)(X + 16 * stile + 4 * g); }
; #pragma unroll
;                 for (int r = 0; r < 4; ++r) { const int s = 16 * stile + 4 * g + r; float v = acc[r]; if (KIND) v *= __expf(fminf(cs[r] - mt, 0.f)); p[r] = (s <= t) ? v : 0.f; rs += p[r]; }
;                 u32x2 pw; pw.x = pk2(p[0], p[1]); pw.y = pk2(p[2], p[3]); *(LAS u32x2*)(PS + t * PST + 16 * stile + 4 * g) = pw;
;                 if (KIND) { rs += __shfl_xor(rs, 16); rs += __shfl_xor(rs, 32); if (g == 0) X[640 + stile * 64 + t] = rs; }
;             }
;             if (KIND) { const int t = tid & 63, part = tid >> 6; float s = 0.f;
; #pragma unroll
;                 for (int i = 0; i < 4; ++i) { const u32x4 qv = *(const LAS u32x4*)(QS + t * QST + 32 * part + 8 * i); const LAS float* nn = X + 384 + 32 * part + 8 * i;
;                     s += bflo(qv.x) * nn[0] + bfhi(qv.x) * nn[1] + bflo(qv.y) * nn[2] + bfhi(qv.y) * nn[3] + bflo(qv.z) * nn[4] + bfhi(qv.z) * nn[5] + bflo(qv.w) * nn[6] + bfhi(qv.w) * nn[7]; }
;                 X[896 + part * 64 + t] = s; }
;         }
;         if (MODE == 1) __syncthreads();
;         {
;             bf16x8 vf[2];
; #pragma unroll
;             for (int ks = 0; ks < 2; ++ks) { const LAS unsigned short* vp = VS + (32 * ks + 8 * g + (li >> 2)) * VST + 16 * w + 4 * (li & 3); vf[ks] = cat8(tr_read(vp), tr_read(vp + 4 * VST)); }
;             bf16x8 sf[NSL];
; #pragma unroll
;             for (int i = 0; i < NSL; ++i) sf[i] = pack8(S[2 * i], S[2 * i + 1]);
.LBB0_534:
	s_or_b64 exec, exec, s[0:1]
	s_waitcnt lgkmcnt(1)
	ds_read_b128 v[68:71], v120 offset:33792
	ds_read_b128 v[72:75], v205 offset:8448
	s_waitcnt lgkmcnt(0)
	v_mfma_f32_16x16x32_bf16 v[68:71], v[68:71], v[72:75], 0
	ds_read_b128 v[72:75], v120 offset:33856
	ds_read_b128 v[76:79], v205 offset:8512
	s_waitcnt lgkmcnt(0)
	v_mfma_f32_16x16x32_bf16 v[68:71], v[72:75], v[76:79], v[68:71]
	ds_read_b128 v[72:75], v120 offset:33920
	ds_read_b128 v[76:79], v205 offset:8576
	s_waitcnt lgkmcnt(0)
	v_mfma_f32_16x16x32_bf16 v[68:71], v[72:75], v[76:79], v[68:71]
	ds_read_b128 v[72:75], v120 offset:33984
	ds_read_b128 v[76:79], v205 offset:8640
	s_waitcnt lgkmcnt(0)
	v_mfma_f32_16x16x32_bf16 v[68:71], v[72:75], v[76:79], v[68:71]
	ds_read_b128 v[72:75], v120 offset:34048
	ds_read_b128 v[76:79], v205 offset:8704
	s_waitcnt lgkmcnt(0)
	v_mfma_f32_16x16x32_bf16 v[68:71], v[72:75], v[76:79], v[68:71]
	ds_read_b128 v[72:75], v120 offset:34112
	ds_read_b128 v[76:79], v205 offset:8768
	s_waitcnt lgkmcnt(0)
	v_mfma_f32_16x16x32_bf16 v[68:71], v[72:75], v[76:79], v[68:71]
	ds_read_b128 v[72:75], v120 offset:34176
	ds_read_b128 v[76:79], v205 offset:8832
	s_waitcnt lgkmcnt(0)
	v_mfma_f32_16x16x32_bf16 v[68:71], v[72:75], v[76:79], v[68:71]
	ds_read_b128 v[72:75], v120 offset:34240
	ds_read_b128 v[76:79], v205 offset:8896
	s_waitcnt lgkmcnt(0)
	v_mfma_f32_16x16x32_bf16 v[68:71], v[72:75], v[76:79], v[68:71]
	ds_read_b32 v0, v182 offset:256
	ds_read_b128 v[72:75], v121
	s_waitcnt lgkmcnt(0)
	v_sub_f32_e32 v72, v72, v0
	v_min_f32_e32 v72, 0, v72
	v_sub_f32_e32 v73, v73, v0
	v_mul_f32_e32 v72, 0x3fb8aa3b, v72
	v_min_f32_e32 v73, 0, v73
	v_exp_f32_e32 v72, v72
	v_mul_f32_e32 v73, 0x3fb8aa3b, v73
	v_exp_f32_e32 v73, v73
	v_mul_f32_e32 v68, v68, v72
	v_cndmask_b32_e64 v72, v68, 0, s[34:35]
	v_mul_f32_e32 v69, v69, v73
	v_add_f32_e32 v68, 0, v72
	v_cndmask_b32_e64 v73, 0, v69, s[36:37]
	v_add_f32_e32 v76, v73, v68
	v_sub_f32_e32 v68, v74, v0
	v_sub_f32_e32 v0, v75, v0
	v_min_f32_e32 v68, 0, v68
	v_min_f32_e32 v0, 0, v0
	v_mul_f32_e32 v68, 0x3fb8aa3b, v68
	v_mul_f32_e32 v0, 0x3fb8aa3b, v0
	v_exp_f32_e32 v68, v68
	v_exp_f32_e32 v69, v0
	s_nop 0
	v_pk_mul_f32 v[68:69], v[70:71], v[68:69]
	v_cndmask_b32_e64 v68, v68, 0, s[40:41]
	v_cvt_pk_bf16_f32 v72, v72, v73
	v_cndmask_b32_e64 v0, v69, 0, s[38:39]
	v_and_b32_sdwa v71, v68, v224 dst_sel:DWORD dst_unused:UNUSED_PAD src0_sel:WORD_1 src1_sel:DWORD
	v_add_f32_e32 v69, v68, v76
	v_and_b32_sdwa v70, v0, v224 dst_sel:DWORD dst_unused:UNUSED_PAD src0_sel:WORD_1 src1_sel:DWORD
	v_add3_u32 v68, v68, v71, s81
	v_add_f32_e32 v69, v0, v69
	v_add3_u32 v0, v0, v70, s81
	v_lshrrev_b32_e32 v68, 16, v68
	v_and_or_b32 v73, v0, s46, v68
	ds_bpermute_b32 v0, v128, v69
	ds_write_b64 v206, v[72:73] offset:2304
	s_waitcnt lgkmcnt(1)
	v_add_f32_e32 v0, v69, v0
	ds_bpermute_b32 v68, v129, v0
	s_and_saveexec_b64 s[0:1], s[12:13]
	s_cbranch_execz .LBB0_536
	s_waitcnt lgkmcnt(0)
	v_add_f32_e32 v0, v0, v68
	ds_write_b32 v181, v0 offset:2624
.LBB0_536:
	s_or_b64 exec, exec, s[0:1]
	s_waitcnt lgkmcnt(0)
	ds_read_b128 v[68:71], v130
	ds_read_b128 v[72:75], v130 offset:16
	ds_read_b128 v[76:79], v130 offset:32
	ds_read_b128 v[80:83], v130 offset:48
	ds_read_b128 v[84:87], v131
	ds_read_b128 v[88:91], v131 offset:16
	ds_read_b128 v[92:95], v131 offset:32
	ds_read_b128 v[96:99], v131 offset:48
	s_waitcnt lgkmcnt(7)
	v_and_b32_e32 v104, 0xffff0000, v68
	s_waitcnt lgkmcnt(6)
	v_and_b32_e32 v105, 0xffff0000, v72
	v_lshlrev_b32_e32 v101, 16, v72
	s_waitcnt lgkmcnt(1)
	v_mov_b32_e32 v103, v92
	v_mov_b32_e32 v92, v85
	v_lshlrev_b32_e32 v100, 16, v68
	v_mov_b32_e32 v102, v84
	v_pk_mul_f32 v[84:85], v[92:93], v[104:105]
	v_lshlrev_b32_e32 v93, 16, v73
	v_pk_fma_f32 v[84:85], v[102:103], v[100:101], v[84:85]
	v_lshlrev_b32_e32 v92, 16, v69
	v_mov_b32_e32 v100, v86
	v_mov_b32_e32 v101, v94
	v_pk_fma_f32 v[84:85], v[100:101], v[92:93], v[84:85]
	v_and_b32_e32 v73, 0xffff0000, v73
	v_and_b32_e32 v72, 0xffff0000, v69
	v_mov_b32_e32 v94, v87
	v_pk_fma_f32 v[68:69], v[94:95], v[72:73], v[84:85]
	v_lshlrev_b32_e32 v73, 16, v74
	v_lshlrev_b32_e32 v72, 16, v70
	v_mov_b32_e32 v84, v88
	s_waitcnt lgkmcnt(0)
	v_mov_b32_e32 v85, v96
	v_pk_fma_f32 v[68:69], v[84:85], v[72:73], v[68:69]
	v_and_b32_e32 v73, 0xffff0000, v74
	v_and_b32_e32 v72, 0xffff0000, v70
	v_mov_b32_e32 v96, v89
	v_pk_fma_f32 v[68:69], v[96:97], v[72:73], v[68:69]
	v_lshlrev_b32_e32 v73, 16, v75
	v_lshlrev_b32_e32 v72, 16, v71
	v_mov_b32_e32 v84, v90
	v_mov_b32_e32 v85, v98
	v_pk_fma_f32 v[68:69], v[84:85], v[72:73], v[68:69]
	v_and_b32_e32 v73, 0xffff0000, v75
	v_and_b32_e32 v72, 0xffff0000, v71
	v_mov_b32_e32 v98, v91
	v_pk_fma_f32 v[68:69], v[98:99], v[72:73], v[68:69]
	v_and_b32_e32 v97, 0xffff0000, v80
	v_add_f32_e32 v0, 0, v68
	v_add_f32_e32 v0, v0, v69
	ds_read_b128 v[68:71], v131 offset:80
	ds_read_b128 v[72:75], v131 offset:112
	ds_read_b128 v[84:87], v131 offset:64
	ds_read_b128 v[88:91], v131 offset:96
	v_and_b32_e32 v96, 0xffff0000, v76
	v_lshlrev_b32_e32 v93, 16, v80
	v_lshlrev_b32_e32 v92, 16, v76
	s_waitcnt lgkmcnt(1)
	v_mov_b32_e32 v94, v84
	s_waitcnt lgkmcnt(0)
	v_mov_b32_e32 v95, v88
	v_mov_b32_e32 v88, v85
	v_pk_mul_f32 v[84:85], v[88:89], v[96:97]
	v_lshlrev_b32_e32 v89, 16, v81
	v_pk_fma_f32 v[84:85], v[94:95], v[92:93], v[84:85]
	v_lshlrev_b32_e32 v88, 16, v77
	v_mov_b32_e32 v92, v86
	v_mov_b32_e32 v93, v90
	v_pk_fma_f32 v[84:85], v[92:93], v[88:89], v[84:85]
	v_and_b32_e32 v81, 0xffff0000, v81
	v_and_b32_e32 v80, 0xffff0000, v77
	v_mov_b32_e32 v90, v87
	v_pk_fma_f32 v[76:77], v[90:91], v[80:81], v[84:85]
	v_lshlrev_b32_e32 v81, 16, v82
	v_lshlrev_b32_e32 v80, 16, v78
	v_mov_b32_e32 v84, v68
	v_mov_b32_e32 v85, v72
	v_pk_fma_f32 v[76:77], v[84:85], v[80:81], v[76:77]
	v_and_b32_e32 v81, 0xffff0000, v82
	v_and_b32_e32 v80, 0xffff0000, v78
	v_mov_b32_e32 v72, v69
	v_pk_fma_f32 v[68:69], v[72:73], v[80:81], v[76:77]
	v_lshlrev_b32_e32 v73, 16, v83
	v_lshlrev_b32_e32 v72, 16, v79
	v_mov_b32_e32 v76, v70
	v_mov_b32_e32 v77, v74
	v_pk_fma_f32 v[68:69], v[76:77], v[72:73], v[68:69]
	v_and_b32_e32 v73, 0xffff0000, v83
	v_and_b32_e32 v72, 0xffff0000, v79
	v_mov_b32_e32 v74, v71
	v_pk_fma_f32 v[68:69], v[74:75], v[72:73], v[68:69]
	v_add_f32_e32 v0, v0, v68
	v_add_f32_e32 v0, v0, v69
	ds_write_b32 v132, v0 offset:3584
	v_cvt_pk_bf16_f32 v76, v24, v25
	v_cvt_pk_bf16_f32 v77, v26, v27
	v_cvt_pk_bf16_f32 v78, v4, v5
	v_cvt_pk_bf16_f32 v79, v6, v7
	v_cvt_pk_bf16_f32 v80, v60, v61
	v_cvt_pk_bf16_f32 v81, v62, v63
	v_cvt_pk_bf16_f32 v82, v8, v9
	v_cvt_pk_bf16_f32 v83, v10, v11
	v_cvt_pk_bf16_f32 v84, v12, v13
	v_cvt_pk_bf16_f32 v85, v14, v15
	v_cvt_pk_bf16_f32 v86, v16, v17
	v_cvt_pk_bf16_f32 v87, v18, v19
	v_cvt_pk_bf16_f32 v88, v20, v21
	v_cvt_pk_bf16_f32 v89, v22, v23
	v_cvt_pk_bf16_f32 v90, v28, v29
	v_cvt_pk_bf16_f32 v91, v30, v31
	v_cvt_pk_bf16_f32 v92, v32, v33
	v_cvt_pk_bf16_f32 v93, v34, v35
	v_cvt_pk_bf16_f32 v94, v36, v37
	v_cvt_pk_bf16_f32 v95, v38, v39
	s_waitcnt lgkmcnt(0)
	s_barrier
; #define LAS __attribute__((address_space(3)))
; __device__ __forceinline__ unsigned pk2(float lo, float hi) { return f2bf(lo) | (f2bf(hi) << 16); }
; #define MFMA16(a, b, c) __builtin_amdgcn_mfma_f32_16x16x32_bf16((a), (b), (c), 0, 0, 0)
; __device__ __forceinline__ s16x4 tr_read(const LAS unsigned short* p) { return __builtin_amdgcn_ds_read_tr16_b64_v4i16((LAS s16x4*)p); }
; template <int KIND, int MODE>
; __device__ __forceinline__ void scan_unit(Frame& F, int layer, int h, int vhalf, int grp) {
;     ...
;             for (int ks = 0; ks < 2; ++ks) { const LAS unsigned short* vp = VS + (32 * ks + 8 * g + (li >> 2)) * VST + 16 * w + 4 * (li & 3); vf[ks] = cat8(tr_read(vp), tr_read(vp + 4 * VST)); }
;             bf16x8 sf[NSL];
; #pragma unroll
;             for (int i = 0; i < NSL; ++i) sf[i] = pack8(S[2 * i], S[2 * i + 1]);
;             if (MODE == 1)
; #pragma unroll
;             for (int tt = 0; tt < 4; ++tt) { const int t = 16 * tt + li; f32x4 oi = (f32x4){0.f, 0.f, 0.f, 0.f}, oe = (f32x4){0.f, 0.f, 0.f, 0.f};
; #pragma unroll
;                 for (int ks = 0; ks < 2; ++ks) { const bf16x8 pb = *(const LAS bf16x8*)(PS + t * PST + 32 * ks + 8 * g); oi = MFMA16(vf[ks], pb, oi); }
; #pragma unroll
;                 for (int i = 0; i < NSL; ++i) { const u32x2 q0 = *(const LAS u32x2*)(QS + t * QST + 32 * i + 4 * g), q1 = *(const LAS u32x2*)(QS + t * QST + 32 * i + 16 + 4 * g);
;                     const bf16x8 qb = __builtin_bit_cast(bf16x8, ((u32x4){q0.x, q0.y, q1.x, q1.y})); oe = MFMA16(sf[i], qb, oe); }
;                 f32x4 o;
;                 if (KIND) { const float wi = X[128 + t]; float qn = wi * (((X[896 + t] + X[960 + t]) + (X[1024 + t] + X[1088 + t])) + ((X[1152 + t] + X[1216 + t]) + (X[1280 + t] + X[1344 + t])));
;                     qn += (X[640 + t] + X[704 + t]) + (X[768 + t] + X[832 + t]);
;                     const float inv = 1.0f / fmaxf(fabsf(qn), X[256 + t]); o = (oi + oe * wi) * inv; }
;                 else o = oi + oe;
;                 u32x2 ow; ow.x = pk2(o[0], o[1]); ow.y = pk2(o[2], o[3]); *(u32x2*)(yout + (size_t)(tb + t) * D) = ow;
;                 float sq = (o[0] * o[0] + o[1] * o[1]) + (o[2] * o[2] + o[3] * o[3]); sq += __shfl_xor(sq, 16); sq += __shfl_xor(sq, 32);
;                 if (g == 0) SSR[w * 64 + t] = sq;
	ds_read_b64_tr_b16 v[72:73], v198
	ds_read_b64_tr_b16 v[74:75], v198 offset:1088
	ds_read_b64_tr_b16 v[68:69], v198 offset:8704
	ds_read_b64_tr_b16 v[70:71], v198 offset:9792
	ds_read_b128 v[108:111], v199
	ds_read_b128 v[112:115], v199 offset:64
	ds_read2_b64 v[208:211], v183 offset1:4
	v_cvt_pk_bf16_f32 v96, v40, v41
	v_cvt_pk_bf16_f32 v97, v42, v43
	ds_read2_b64 v[212:215], v183 offset0:8 offset1:12
	s_waitcnt lgkmcnt(1)
	v_mfma_f32_16x16x32_bf16 v[208:211], v[76:79], v[208:211], 0
	v_cvt_pk_bf16_f32 v98, v44, v45
	s_waitcnt lgkmcnt(0)
	v_mfma_f32_16x16x32_bf16 v[208:211], v[80:83], v[212:215], v[208:211]
	ds_read2_b64 v[212:215], v183 offset0:16 offset1:20
	v_cvt_pk_bf16_f32 v99, v46, v47
	v_cvt_pk_bf16_f32 v100, v48, v49
	s_waitcnt lgkmcnt(0)
	v_mfma_f32_16x16x32_bf16 v[208:211], v[84:87], v[212:215], v[208:211]
	ds_read2_b64 v[212:215], v183 offset0:24 offset1:28
	v_cvt_pk_bf16_f32 v101, v50, v51
	v_cvt_pk_bf16_f32 v102, v52, v53
	s_waitcnt lgkmcnt(0)
	v_mfma_f32_16x16x32_bf16 v[208:211], v[88:91], v[212:215], v[208:211]
	ds_read2_b64 v[212:215], v183 offset0:32 offset1:36
	v_cvt_pk_bf16_f32 v103, v54, v55
	s_waitcnt lgkmcnt(0)
	v_mfma_f32_16x16x32_bf16 v[208:211], v[92:95], v[212:215], v[208:211]
	ds_read2_b64 v[212:215], v183 offset0:40 offset1:44
	v_cvt_pk_bf16_f32 v104, v56, v57
	v_cvt_pk_bf16_f32 v105, v58, v59
	s_waitcnt lgkmcnt(0)
	v_mfma_f32_16x16x32_bf16 v[208:211], v[96:99], v[212:215], v[208:211]
	ds_read2_b64 v[212:215], v183 offset0:48 offset1:52
	v_cvt_pk_bf16_f32 v106, v64, v65
	v_cvt_pk_bf16_f32 v107, v66, v67
	s_waitcnt lgkmcnt(0)
	v_mfma_f32_16x16x32_bf16 v[208:211], v[100:103], v[212:215], v[208:211]
	ds_read2_b64 v[212:215], v183 offset0:56 offset1:60
	v_mfma_f32_16x16x32_bf16 v[108:111], v[72:75], v[108:111], 0
	s_waitcnt lgkmcnt(0)
	v_mfma_f32_16x16x32_bf16 v[208:211], v[104:107], v[212:215], v[208:211]
	v_mfma_f32_16x16x32_bf16 v[108:111], v[68:71], v[112:115], v[108:111]
	ds_read2st64_b32 v[112:113], v184 offset0:2 offset1:4
	ds_read2st64_b32 v[114:115], v184 offset0:14 offset1:15
	ds_read2st64_b32 v[166:167], v184 offset0:16 offset1:17
	ds_read2st64_b32 v[212:213], v184 offset0:18 offset1:19
	ds_read2st64_b32 v[214:215], v184 offset0:20 offset1:21
	ds_read2st64_b32 v[216:217], v184 offset0:10 offset1:11
	ds_read2st64_b32 v[218:219], v184 offset0:12 offset1:13
	s_waitcnt lgkmcnt(5)
	v_add_f32_e32 v114, v114, v115
	s_waitcnt lgkmcnt(4)
	v_add_f32_e32 v166, v166, v167
	s_waitcnt lgkmcnt(3)
	v_add_f32_e32 v212, v212, v213
	s_waitcnt lgkmcnt(2)
	v_add_f32_e32 v214, v214, v215
	s_waitcnt lgkmcnt(1)
	v_mov_b32_e32 v115, v216
	v_mov_b32_e32 v167, v217
	s_waitcnt lgkmcnt(0)
	v_mov_b32_e32 v213, v218
	v_mov_b32_e32 v215, v219
	v_pk_add_f32 v[114:115], v[114:115], v[166:167]
	v_pk_add_f32 v[166:167], v[212:213], v[214:215]
	v_max_f32_e32 v0, v113, v113
	v_pk_add_f32 v[114:115], v[114:115], v[166:167]
	s_nop 0
	v_fmac_f32_e32 v115, v112, v114
	v_max_f32_e64 v0, |v115|, v0
	v_div_scale_f32 v113, s[0:1], v0, v0, 1.0
	v_rcp_f32_e32 v114, v113
	s_nop 0
	v_fma_f32 v115, -v113, v114, 1.0
	v_fmac_f32_e32 v114, v115, v114
	v_div_scale_f32 v115, vcc, 1.0, v0, 1.0
	v_mul_f32_e32 v166, v115, v114
	v_fma_f32 v167, -v113, v166, v115
	v_fmac_f32_e32 v166, v167, v114
	v_fma_f32 v113, -v113, v166, v115
	v_div_fmas_f32 v113, v113, v114, v166
	v_div_fixup_f32 v0, v113, v0, 1.0
	v_pk_fma_f32 v[110:111], v[210:211], v[112:113], v[110:111] op_sel_hi:[1,0,1]
	v_pk_fma_f32 v[108:109], v[208:209], v[112:113], v[108:109] op_sel_hi:[1,0,1]
	v_pk_mul_f32 v[110:111], v[110:111], v[0:1] op_sel_hi:[1,0]
	v_pk_mul_f32 v[108:109], v[108:109], v[0:1] op_sel_hi:[1,0]
	v_and_b32_sdwa v113, v111, v224 dst_sel:DWORD dst_unused:UNUSED_PAD src0_sel:WORD_1 src1_sel:DWORD
	v_and_b32_sdwa v0, v110, v224 dst_sel:DWORD dst_unused:UNUSED_PAD src0_sel:WORD_1 src1_sel:DWORD
	v_add3_u32 v113, v111, v113, s81
	v_add3_u32 v0, v110, v0, s81
	v_and_b32_e32 v113, 0xffff0000, v113
	v_and_b32_sdwa v112, v108, v224 dst_sel:DWORD dst_unused:UNUSED_PAD src0_sel:WORD_1 src1_sel:DWORD
	v_or_b32_sdwa v113, v113, v0 dst_sel:DWORD dst_unused:UNUSED_PAD src0_sel:DWORD src1_sel:WORD_1
	v_mul_f32_e32 v0, v109, v109
	v_add3_u32 v112, v108, v112, s81
	v_fmac_f32_e32 v0, v108, v108
	v_mul_f32_e32 v108, v111, v111
	v_fmac_f32_e32 v108, v110, v110
	v_add_f32_e32 v0, v0, v108
	ds_bpermute_b32 v108, v128, v0
	v_and_b32_sdwa v114, v109, v224 dst_sel:DWORD dst_unused:UNUSED_PAD src0_sel:WORD_1 src1_sel:DWORD
	v_add3_u32 v114, v109, v114, s81
	v_and_b32_e32 v114, 0xffff0000, v114
	v_or_b32_sdwa v112, v114, v112 dst_sel:DWORD dst_unused:UNUSED_PAD src0_sel:DWORD src1_sel:WORD_1
	s_waitcnt lgkmcnt(0)
	v_add_f32_e32 v0, v0, v108
	ds_bpermute_b32 v108, v129, v0
	v_or_b32_e32 v114, s44, v117
	v_ashrrev_i32_e32 v115, 31, v114
	v_lshlrev_b64 v[114:115], 11, v[114:115]
	v_lshl_add_u64 v[114:115], v[2:3], 0, v[114:115]
	flat_store_dwordx2 v[114:115], v[112:113]
	s_and_saveexec_b64 s[0:1], s[12:13]
	s_cbranch_execz .LBB0_538
	s_waitcnt lgkmcnt(0)
	v_add_f32_e32 v0, v0, v108
	ds_write_b32 v185, v0

; #define LAS __attribute__((address_space(3)))
; template <int KIND, int MODE>
; __device__ __forceinline__ void scan_unit(Frame& F, int layer, int h, int vhalf, int grp) {
;     ...
;             for (int tt = 0; tt < 2; ++tt) { const int ttile = 2 * (w & 1) + tt; f32x4 acc = (f32x4){0.f, 0.f, 0.f, 0.f};
; #pragma unroll
;                 for (int sl = 0; sl < NSL; ++sl) { const bf16x8 a = *(const LAS bf16x8*)(KS + (16 * stile + li) * QST + 32 * sl + 8 * g), bb = *(const LAS bf16x8*)(QS + (16 * ttile + li) * QST + 32 * sl + 8 * g); acc = MFMA16(a, bb, acc); }
;                 const int t = 16 * ttile + li; float p[4]; float rs = 0.f;
;                 float mt = 0.f; f32x4 cs = (f32x4){0.f, 0.f, 0.f, 0.f};
;                 if (KIND) { mt = X[64 + t]; cs = *(const LAS f32x4*)(X + 16 * stile + 4 * g); }
; #pragma unroll
;                 for (int r = 0; r < 4; ++r) { const int s = 16 * stile + 4 * g + r; float v = acc[r]; if (KIND) v *= __expf(fminf(cs[r] - mt, 0.f)); p[r] = (s <= t) ? v : 0.f; rs += p[r]; }
;                 u32x2 pw; pw.x = pk2(p[0], p[1]); pw.y = pk2(p[2], p[3]); *(LAS u32x2*)(PS + t * PST + 16 * stile + 4 * g) = pw;
;     ...
;             for (int ks = 0; ks < 2; ++ks) { const LAS unsigned short* vp = VS + (32 * ks + 8 * g + (li >> 2)) * VST + 16 * w + 4 * (li & 3); vf[ks] = cat8(tr_read(vp), tr_read(vp + 4 * VST)); }
;             bf16x8 sf[NSL];
; #pragma unroll
;             for (int i = 0; i < NSL; ++i) sf[i] = pack8(S[2 * i], S[2 * i + 1]);
;             if (MODE == 1)
; #pragma unroll
;             for (int tt = 0; tt < 4; ++tt) { const int t = 16 * tt + li; f32x4 oi = (f32x4){0.f, 0.f, 0.f, 0.f}, oe = (f32x4){0.f, 0.f, 0.f, 0.f};
; #pragma unroll
;                 for (int ks = 0; ks < 2; ++ks) { const bf16x8 pb = *(const LAS bf16x8*)(PS + t * PST + 32 * ks + 8 * g); oi = MFMA16(vf[ks], pb, oi); }
; #pragma unroll
;                 for (int i = 0; i < NSL; ++i) { const u32x2 q0 = *(const LAS u32x2*)(QS + t * QST + 32 * i + 4 * g), q1 = *(const LAS u32x2*)(QS + t * QST + 32 * i + 16 + 4 * g);
;                     const bf16x8 qb = __builtin_bit_cast(bf16x8, ((u32x4){q0.x, q0.y, q1.x, q1.y})); oe = MFMA16(sf[i], qb, oe); }
;                 f32x4 o;
;                 if (KIND) { const float wi = X[128 + t]; float qn = wi * (((X[896 + t] + X[960 + t]) + (X[1024 + t] + X[1088 + t])) + ((X[1152 + t] + X[1216 + t]) + (X[1280 + t] + X[1344 + t])));
.LBB0_562:
	s_waitcnt lgkmcnt(0)
	s_barrier
	ds_read_b128 v[58:61], v88 offset:33792
	ds_read_b128 v[62:65], v88 offset:33856
	ds_read_b128 v[66:69], v172
	ds_read_b128 v[70:73], v172 offset:64
	s_waitcnt lgkmcnt(0)
	v_mfma_f32_16x16x32_bf16 v[58:61], v[58:61], v[66:69], 0
	ds_read_b128 v[66:69], v88 offset:33920
	ds_read_b128 v[74:77], v88 offset:33984
	s_waitcnt lgkmcnt(2)
	v_mfma_f32_16x16x32_bf16 v[58:61], v[62:65], v[70:73], v[58:61]
	ds_read_b128 v[62:65], v172 offset:128
	ds_read_b128 v[70:73], v172 offset:192
	s_waitcnt lgkmcnt(0)
	v_mfma_f32_16x16x32_bf16 v[58:61], v[66:69], v[62:65], v[58:61]
	s_waitcnt lgkmcnt(0)
	v_mfma_f32_16x16x32_bf16 v[58:61], v[74:77], v[70:73], v[58:61]
	v_and_b32_e32 v93, 64, v225
	v_add_u32_e32 v93, 64, v93
	s_nop 2
	s_nop 2
	v_cndmask_b32_e64 v58, v58, 0, s[22:23]
	v_cndmask_b32_e64 v60, v60, 0, s[26:27]
	v_cndmask_b32_e64 v59, 0, v59, s[24:25]
	v_cndmask_b32_e64 v61, v61, 0, s[28:29]
	v_cvt_pk_bf16_f32 v58, v58, v59
	v_cvt_pk_bf16_f32 v59, v60, v61
	ds_write_b64 v173, v[58:59]
	ds_read_b128 v[58:61], v88 offset:33792
	ds_read_b128 v[62:65], v88 offset:33856
	ds_read_b128 v[66:69], v172 offset:4352
	ds_read_b128 v[70:73], v172 offset:4416
	s_waitcnt lgkmcnt(0)
	v_mfma_f32_16x16x32_bf16 v[58:61], v[58:61], v[66:69], 0
	ds_read_b128 v[66:69], v88 offset:33920
	ds_read_b128 v[74:77], v88 offset:33984
	s_waitcnt lgkmcnt(2)
	v_mfma_f32_16x16x32_bf16 v[58:61], v[62:65], v[70:73], v[58:61]
	ds_read_b128 v[62:65], v172 offset:4480
	ds_read_b128 v[70:73], v172 offset:4544
	s_waitcnt lgkmcnt(0)
	v_mfma_f32_16x16x32_bf16 v[58:61], v[66:69], v[62:65], v[58:61]
	v_cvt_pk_bf16_f32 v66, v10, v11
	v_cvt_pk_bf16_f32 v67, v12, v13
	v_cvt_pk_bf16_f32 v68, v2, v3
	s_waitcnt lgkmcnt(0)
	v_mfma_f32_16x16x32_bf16 v[58:61], v[74:77], v[70:73], v[58:61]
	v_cvt_pk_bf16_f32 v69, v4, v5
	v_cvt_pk_bf16_f32 v70, v30, v31
	v_cvt_pk_bf16_f32 v71, v32, v33
	v_cvt_pk_bf16_f32 v72, v22, v23
	v_cvt_pk_bf16_f32 v73, v24, v25
	v_cvt_pk_bf16_f32 v74, v6, v7
	s_nop 1
	v_cndmask_b32_e64 v58, v58, 0, s[30:31]
	v_cndmask_b32_e64 v60, v60, 0, s[36:37]
	v_cvt_pk_bf16_f32 v75, v8, v9
	v_cndmask_b32_e64 v59, 0, v59, s[34:35]
	v_cndmask_b32_e64 v61, v61, 0, s[38:39]
	v_cvt_pk_bf16_f32 v76, v18, v19
	v_cvt_pk_bf16_f32 v58, v58, v59
	v_cvt_pk_bf16_f32 v59, v60, v61
	ds_write_b64 v173, v[58:59] offset:2304
	s_waitcnt lgkmcnt(0)
	s_barrier
	ds_read_b64_tr_b16 v[62:63], v174
	ds_read_b64_tr_b16 v[64:65], v174 offset:1088
	ds_read_b64_tr_b16 v[58:59], v174 offset:8704
	ds_read_b64_tr_b16 v[60:61], v174 offset:9792
	ds_read2_b64 v[178:181], v142 offset1:4
	v_cvt_pk_bf16_f32 v77, v20, v21
	v_cvt_pk_bf16_f32 v78, v14, v15
	ds_read2_b64 v[182:185], v142 offset0:8 offset1:12
	s_waitcnt lgkmcnt(0)
	v_mfma_f32_16x16x32_bf16 v[178:181], v[66:69], v[178:181], 0
	v_cvt_pk_bf16_f32 v79, v16, v17
	ds_read2_b64 v[186:189], v142 offset0:16 offset1:20
	s_waitcnt lgkmcnt(1)
	v_mfma_f32_16x16x32_bf16 v[178:181], v[70:73], v[182:185], v[178:181]
	v_cvt_pk_bf16_f32 v80, v26, v27
	v_cvt_pk_bf16_f32 v81, v28, v29
	ds_read2_b64 v[182:185], v142 offset0:24 offset1:28
	s_waitcnt lgkmcnt(0)
	v_mfma_f32_16x16x32_bf16 v[178:181], v[74:77], v[186:189], v[178:181]
	ds_read_b128 v[186:189], v176
	ds_read_b128 v[190:193], v176 offset:64
	v_xor_b32_e32 v92, 16, v225
	s_waitcnt lgkmcnt(2)
	v_mfma_f32_16x16x32_bf16 v[180:183], v[78:81], v[182:185], v[178:181]
	v_cmp_lt_i32_e32 vcc, v92, v93
	s_waitcnt lgkmcnt(0)
	v_mfma_f32_16x16x32_bf16 v[184:187], v[62:65], v[186:189], 0
	v_cndmask_b32_e32 v92, v225, v92, vcc
	v_lshlrev_b32_e32 v177, 2, v92
	v_xor_b32_e32 v92, 32, v225
	s_waitcnt lgkmcnt(0)
	v_mfma_f32_16x16x32_bf16 v[184:187], v[58:61], v[190:193], v[184:187]
	v_cmp_lt_i32_e32 vcc, v92, v93
	s_nop 1
	v_cndmask_b32_e32 v92, v225, v92, vcc
	v_lshlrev_b32_e32 v178, 2, v92
	s_nop 2
	v_pk_add_f32 v[92:93], v[182:183], v[186:187]
	v_pk_add_f32 v[166:167], v[180:181], v[184:185]
	v_and_b32_sdwa v181, v93, v224 dst_sel:DWORD dst_unused:UNUSED_PAD src0_sel:WORD_1 src1_sel:DWORD
	v_and_b32_sdwa v182, v167, v224 dst_sel:DWORD dst_unused:UNUSED_PAD src0_sel:WORD_1 src1_sel:DWORD
	v_add3_u32 v181, v93, v181, s81
	v_add3_u32 v182, v167, v182, s81
	v_mul_f32_e32 v167, v167, v167
	v_mul_f32_e32 v93, v93, v93
	v_fmac_f32_e32 v167, v166, v166
	v_fmac_f32_e32 v93, v92, v92
	v_add_f32_e32 v93, v167, v93
	ds_bpermute_b32 v183, v177, v93
	v_and_b32_sdwa v179, v92, v224 dst_sel:DWORD dst_unused:UNUSED_PAD src0_sel:WORD_1 src1_sel:DWORD
	v_and_b32_sdwa v180, v166, v224 dst_sel:DWORD dst_unused:UNUSED_PAD src0_sel:WORD_1 src1_sel:DWORD
	v_add3_u32 v179, v92, v179, s81
	v_and_b32_e32 v181, 0xffff0000, v181
	v_add3_u32 v180, v166, v180, s81
	v_and_b32_e32 v92, 0xffff0000, v182
	v_or_b32_sdwa v167, v181, v179 dst_sel:DWORD dst_unused:UNUSED_PAD src0_sel:DWORD src1_sel:WORD_1
	s_waitcnt lgkmcnt(0)
	v_add_f32_e32 v179, v93, v183
	v_or_b32_sdwa v166, v92, v180 dst_sel:DWORD dst_unused:UNUSED_PAD src0_sel:DWORD src1_sel:WORD_1
	ds_bpermute_b32 v180, v178, v179
	v_add_u32_e32 v92, s52, v171
	v_ashrrev_i32_e32 v93, 31, v92
	v_lshlrev_b64 v[182:183], 11, v[92:93]
	v_lshl_add_u64 v[182:183], v[82:83], 0, v[182:183]
	flat_store_dwordx2 v[182:183], v[166:167]
	s_and_saveexec_b64 s[0:1], s[10:11]
	s_cbranch_execz .LBB0_564
	s_waitcnt lgkmcnt(0)
	v_add_f32_e32 v93, v179, v180
	ds_write_b32 v143, v93
